# v24: HGRN pass B fold loop software-pipelined by one segment (second register set, 72 loads in flight)
# baseline (speedup 1.0000x reference)
; template <bool PA>
; __device__ __forceinline__ void hgrn_scan(unsigned char* lds, const bf16* Q, const bf16* FFb, const bf16* FBb, const bf16* Ib, bf16* OFb, bf16* OBb, const float* lbp, float* segm, int slab, int tid) {
;     ...
;             for (int gg = 0; gg < g; ++gg) { const float* Psi = segm + (size_t)(strm * G + gg) * 16512; const float* Gv = Psi + 16384;
; #pragma unroll
;                 for (int e = 0; e < 4; ++e) { const int kr = 16 * wave + 4 * kq + e; const float gk = Gv[kr];
; #pragma unroll
;                     for (int vt = 0; vt < 8; ++vt) S[vt][e] = gk * S[vt][e] + Psi[kr * 128 + 16 * vt + r16]; } }
.LBB0_671:
	s_mul_i32 s15, s11, 0x10200
	s_mul_hi_i32 s13, s11, 0x10200
	s_add_u32 s18, s2, s15
	s_addc_u32 s19, s58, s13
	v_lshl_add_u64 v[38:39], v[68:69], 2, s[18:19]
	s_mov_b32 s13, 0x10000
	v_add_co_u32_e32 v38, vcc, s13, v38
	v_lshl_add_u64 v[40:41], v[76:77], 2, s[18:19]
	v_lshl_add_u64 v[42:43], v[78:79], 2, s[18:19]
	v_addc_co_u32_e32 v39, vcc, 0, v39, vcc
	global_load_dword v44, v[40:41], off
	global_load_dword v46, v[40:41], off offset:64
	global_load_dword v48, v[40:41], off offset:128
	global_load_dword v50, v[40:41], off offset:192
	global_load_dword v52, v[40:41], off offset:256
	global_load_dword v54, v[40:41], off offset:320
	global_load_dword v56, v[40:41], off offset:384
	global_load_dword v58, v[40:41], off offset:448
	global_load_dword v45, v[40:41], off offset:512
	global_load_dword v47, v[40:41], off offset:576
	global_load_dword v49, v[40:41], off offset:640
	global_load_dword v51, v[40:41], off offset:704
	global_load_dword v53, v[40:41], off offset:768
	global_load_dword v55, v[40:41], off offset:832
	global_load_dword v57, v[40:41], off offset:896
	global_load_dword v59, v[40:41], off offset:960
	global_load_dword v60, v[42:43], off offset:192
	global_load_dword v62, v[42:43], off offset:256
	global_load_dword v64, v[42:43], off offset:320
	global_load_dword v82, v[42:43], off offset:384
	global_load_dword v84, v[42:43], off offset:448
	global_load_dword v87, v[40:41], off offset:1536
	global_load_dword v147, v[40:41], off offset:1600
	global_load_dword v177, v[40:41], off offset:1664
	global_load_dword v61, v[40:41], off offset:1728
	global_load_dword v63, v[40:41], off offset:1792
	global_load_dword v65, v[40:41], off offset:1856
	global_load_dword v83, v[40:41], off offset:1920
	global_load_dword v85, v[40:41], off offset:1984
	s_nop 0
	global_load_dwordx4 v[38:41], v[38:39], off
	s_nop 0
	global_load_dword v86, v[42:43], off
	global_load_dword v146, v[42:43], off offset:64
	global_load_dword v176, v[42:43], off offset:128
	s_add_i32 s12, s12, -1
	s_add_i32 s11, s11, 1
.Lhg_fold_top:
	s_cmp_eq_u32 s12, 0
	s_cbranch_scc1 .Lhg_fold_last_a
	s_mul_i32 s15, s11, 0x10200
	s_mul_hi_i32 s13, s11, 0x10200
	s_add_u32 s18, s2, s15
	s_addc_u32 s19, s58, s13
	v_lshl_add_u64 v[204:205], v[68:69], 2, s[18:19]
	s_mov_b32 s13, 0x10000
	v_add_co_u32_e32 v204, vcc, s13, v204
	v_lshl_add_u64 v[206:207], v[76:77], 2, s[18:19]
	v_lshl_add_u64 v[208:209], v[78:79], 2, s[18:19]
	v_addc_co_u32_e32 v205, vcc, 0, v205, vcc
	global_load_dword v210, v[206:207], off
	global_load_dword v212, v[206:207], off offset:64
	global_load_dword v214, v[206:207], off offset:128
	global_load_dword v216, v[206:207], off offset:192
	global_load_dword v218, v[206:207], off offset:256
	global_load_dword v220, v[206:207], off offset:320
	global_load_dword v222, v[206:207], off offset:384
	global_load_dword v224, v[206:207], off offset:448
	global_load_dword v211, v[206:207], off offset:512
	global_load_dword v213, v[206:207], off offset:576
	global_load_dword v215, v[206:207], off offset:640
	global_load_dword v217, v[206:207], off offset:704
	global_load_dword v219, v[206:207], off offset:768
	global_load_dword v221, v[206:207], off offset:832
	global_load_dword v223, v[206:207], off offset:896
	global_load_dword v225, v[206:207], off offset:960
	global_load_dword v226, v[208:209], off offset:192
	global_load_dword v228, v[208:209], off offset:256
	global_load_dword v230, v[208:209], off offset:320
	global_load_dword v232, v[208:209], off offset:384
	global_load_dword v234, v[208:209], off offset:448
	global_load_dword v237, v[206:207], off offset:1536
	global_load_dword v239, v[206:207], off offset:1600
	global_load_dword v241, v[206:207], off offset:1664
	global_load_dword v227, v[206:207], off offset:1728
	global_load_dword v229, v[206:207], off offset:1792
	global_load_dword v231, v[206:207], off offset:1856
	global_load_dword v233, v[206:207], off offset:1920
	global_load_dword v235, v[206:207], off offset:1984
	s_nop 0
	global_load_dwordx4 v[204:207], v[204:205], off
	s_nop 0
	global_load_dword v236, v[208:209], off
	global_load_dword v238, v[208:209], off offset:64
	global_load_dword v240, v[208:209], off offset:128
	s_add_i32 s12, s12, -1
	s_add_i32 s11, s11, 1
	s_waitcnt vmcnt(36)
	v_pk_fma_f32 v[2:3], v[2:3], v[38:39], v[44:45]
	v_pk_fma_f32 v[4:5], v[4:5], v[40:41], v[86:87]
	v_pk_fma_f32 v[8:9], v[8:9], v[40:41], v[146:147]
	v_pk_fma_f32 v[6:7], v[6:7], v[38:39], v[46:47]
	v_pk_fma_f32 v[12:13], v[12:13], v[40:41], v[176:177]
	v_pk_fma_f32 v[10:11], v[10:11], v[38:39], v[48:49]
	v_pk_fma_f32 v[16:17], v[16:17], v[40:41], v[60:61]
	v_pk_fma_f32 v[14:15], v[14:15], v[38:39], v[50:51]
	v_pk_fma_f32 v[20:21], v[20:21], v[40:41], v[62:63]
	v_pk_fma_f32 v[18:19], v[18:19], v[38:39], v[52:53]
	v_pk_fma_f32 v[24:25], v[24:25], v[40:41], v[64:65]
	v_pk_fma_f32 v[22:23], v[22:23], v[38:39], v[54:55]
	v_pk_fma_f32 v[28:29], v[28:29], v[40:41], v[82:83]
	v_pk_fma_f32 v[26:27], v[26:27], v[38:39], v[56:57]
	v_pk_fma_f32 v[32:33], v[32:33], v[40:41], v[84:85]
	v_pk_fma_f32 v[30:31], v[30:31], v[38:39], v[58:59]
	s_cmp_eq_u32 s12, 0
	s_cbranch_scc1 .Lhg_fold_last_b
; template <bool PA>
; __device__ __forceinline__ void hgrn_scan(unsigned char* lds, const bf16* Q, const bf16* FFb, const bf16* FBb, const bf16* Ib, bf16* OFb, bf16* OBb, const float* lbp, float* segm, int slab, int tid) {
;     ...
;             for (int gg = 0; gg < g; ++gg) { const float* Psi = segm + (size_t)(strm * G + gg) * 16512; const float* Gv = Psi + 16384;
; #pragma unroll
;                 for (int e = 0; e < 4; ++e) { const int kr = 16 * wave + 4 * kq + e; const float gk = Gv[kr];
; #pragma unroll
;                     for (int vt = 0; vt < 8; ++vt) S[vt][e] = gk * S[vt][e] + Psi[kr * 128 + 16 * vt + r16]; } }
	s_mul_i32 s15, s11, 0x10200
	s_mul_hi_i32 s13, s11, 0x10200
	s_add_u32 s18, s2, s15
	s_addc_u32 s19, s58, s13
	v_lshl_add_u64 v[38:39], v[68:69], 2, s[18:19]
	s_mov_b32 s13, 0x10000
	v_add_co_u32_e32 v38, vcc, s13, v38
	v_lshl_add_u64 v[40:41], v[76:77], 2, s[18:19]
	v_lshl_add_u64 v[42:43], v[78:79], 2, s[18:19]
	v_addc_co_u32_e32 v39, vcc, 0, v39, vcc
	global_load_dword v44, v[40:41], off
	global_load_dword v46, v[40:41], off offset:64
	global_load_dword v48, v[40:41], off offset:128
	global_load_dword v50, v[40:41], off offset:192
	global_load_dword v52, v[40:41], off offset:256
	global_load_dword v54, v[40:41], off offset:320
	global_load_dword v56, v[40:41], off offset:384
	global_load_dword v58, v[40:41], off offset:448
	global_load_dword v45, v[40:41], off offset:512
	global_load_dword v47, v[40:41], off offset:576
	global_load_dword v49, v[40:41], off offset:640
	global_load_dword v51, v[40:41], off offset:704
	global_load_dword v53, v[40:41], off offset:768
	global_load_dword v55, v[40:41], off offset:832
	global_load_dword v57, v[40:41], off offset:896
	global_load_dword v59, v[40:41], off offset:960
	global_load_dword v60, v[42:43], off offset:192
	global_load_dword v62, v[42:43], off offset:256
	global_load_dword v64, v[42:43], off offset:320
	global_load_dword v82, v[42:43], off offset:384
	global_load_dword v84, v[42:43], off offset:448
	global_load_dword v87, v[40:41], off offset:1536
	global_load_dword v147, v[40:41], off offset:1600
	global_load_dword v177, v[40:41], off offset:1664
	global_load_dword v61, v[40:41], off offset:1728
	global_load_dword v63, v[40:41], off offset:1792
	global_load_dword v65, v[40:41], off offset:1856
	global_load_dword v83, v[40:41], off offset:1920
	global_load_dword v85, v[40:41], off offset:1984
	s_nop 0
	global_load_dwordx4 v[38:41], v[38:39], off
	s_nop 0
	global_load_dword v86, v[42:43], off
	global_load_dword v146, v[42:43], off offset:64
	global_load_dword v176, v[42:43], off offset:128
	s_add_i32 s12, s12, -1
	s_add_i32 s11, s11, 1
	s_waitcnt vmcnt(36)
	v_pk_fma_f32 v[2:3], v[2:3], v[204:205], v[210:211]
	v_pk_fma_f32 v[4:5], v[4:5], v[206:207], v[236:237]
	v_pk_fma_f32 v[8:9], v[8:9], v[206:207], v[238:239]
	v_pk_fma_f32 v[6:7], v[6:7], v[204:205], v[212:213]
	v_pk_fma_f32 v[12:13], v[12:13], v[206:207], v[240:241]
	v_pk_fma_f32 v[10:11], v[10:11], v[204:205], v[214:215]
	v_pk_fma_f32 v[16:17], v[16:17], v[206:207], v[226:227]
	v_pk_fma_f32 v[14:15], v[14:15], v[204:205], v[216:217]
	v_pk_fma_f32 v[20:21], v[20:21], v[206:207], v[228:229]
	v_pk_fma_f32 v[18:19], v[18:19], v[204:205], v[218:219]
	v_pk_fma_f32 v[24:25], v[24:25], v[206:207], v[230:231]
	v_pk_fma_f32 v[22:23], v[22:23], v[204:205], v[220:221]
	v_pk_fma_f32 v[28:29], v[28:29], v[206:207], v[232:233]
	v_pk_fma_f32 v[26:27], v[26:27], v[204:205], v[222:223]
	v_pk_fma_f32 v[32:33], v[32:33], v[206:207], v[234:235]
	v_pk_fma_f32 v[30:31], v[30:31], v[204:205], v[224:225]
	s_branch .Lhg_fold_top
.Lhg_fold_last_a:
	s_waitcnt vmcnt(0)
	v_pk_fma_f32 v[2:3], v[2:3], v[38:39], v[44:45]
	v_pk_fma_f32 v[4:5], v[4:5], v[40:41], v[86:87]
	v_pk_fma_f32 v[8:9], v[8:9], v[40:41], v[146:147]
	v_pk_fma_f32 v[6:7], v[6:7], v[38:39], v[46:47]
	v_pk_fma_f32 v[12:13], v[12:13], v[40:41], v[176:177]
	v_pk_fma_f32 v[10:11], v[10:11], v[38:39], v[48:49]
	v_pk_fma_f32 v[16:17], v[16:17], v[40:41], v[60:61]
	v_pk_fma_f32 v[14:15], v[14:15], v[38:39], v[50:51]
	v_pk_fma_f32 v[20:21], v[20:21], v[40:41], v[62:63]
	v_pk_fma_f32 v[18:19], v[18:19], v[38:39], v[52:53]
	v_pk_fma_f32 v[24:25], v[24:25], v[40:41], v[64:65]
	v_pk_fma_f32 v[22:23], v[22:23], v[38:39], v[54:55]
	v_pk_fma_f32 v[28:29], v[28:29], v[40:41], v[82:83]
	v_pk_fma_f32 v[26:27], v[26:27], v[38:39], v[56:57]
	v_pk_fma_f32 v[32:33], v[32:33], v[40:41], v[84:85]
	v_pk_fma_f32 v[30:31], v[30:31], v[38:39], v[58:59]
	s_branch .LBB0_673
.Lhg_fold_last_b:
	s_waitcnt vmcnt(0)
	v_pk_fma_f32 v[2:3], v[2:3], v[204:205], v[210:211]
	v_pk_fma_f32 v[4:5], v[4:5], v[206:207], v[236:237]
	v_pk_fma_f32 v[8:9], v[8:9], v[206:207], v[238:239]
	v_pk_fma_f32 v[6:7], v[6:7], v[204:205], v[212:213]
	v_pk_fma_f32 v[12:13], v[12:13], v[206:207], v[240:241]
	v_pk_fma_f32 v[10:11], v[10:11], v[204:205], v[214:215]
	v_pk_fma_f32 v[16:17], v[16:17], v[206:207], v[226:227]
	v_pk_fma_f32 v[14:15], v[14:15], v[204:205], v[216:217]
	v_pk_fma_f32 v[20:21], v[20:21], v[206:207], v[228:229]
	v_pk_fma_f32 v[18:19], v[18:19], v[204:205], v[218:219]
	v_pk_fma_f32 v[24:25], v[24:25], v[206:207], v[230:231]
	v_pk_fma_f32 v[22:23], v[22:23], v[204:205], v[220:221]
	v_pk_fma_f32 v[28:29], v[28:29], v[206:207], v[232:233]
	v_pk_fma_f32 v[26:27], v[26:27], v[204:205], v[222:223]
	v_pk_fma_f32 v[32:33], v[32:33], v[206:207], v[234:235]
	v_pk_fma_f32 v[30:31], v[30:31], v[204:205], v[224:225]
	s_branch .LBB0_673
